# grid barrier: waiters poll the cross-XCD arrival counter against (gen+1)*nx instead of the top-generation word (one hop fewer on release), 11 of 12 seams, on top of v14
# baseline (speedup 1.0000x reference)
; __device__ __forceinline__ unsigned xb_ld(unsigned* p)              { return __hip_atomic_load(p, __ATOMIC_RELAXED, __HIP_MEMORY_SCOPE_AGENT); }
; __device__ __forceinline__ unsigned xb_add(unsigned* p, unsigned v) { return __hip_atomic_fetch_add(p, v, __ATOMIC_RELAXED, __HIP_MEMORY_SCOPE_AGENT); }
; #define XB_SPIN(cond, bar) do { unsigned _sp = 0; while (cond) { __builtin_amdgcn_s_sleep(1); \
;     if ((++_sp & 255u) == 0u) { if (xb_ld(&(bar)[XB_TMO])) break; if (_sp > XB_SPIN_CAP) { atomicAdd(&(bar)[XB_TMO], 1u); break; } } } } while (0)
; __device__ __forceinline__ void xcd_barrier(const XcdBarrier& b) {
;     ...
;         const unsigned old = xb_add(&bar[XB_XSUB(b.x)], 1u);
;         const unsigned gen = old / nloc;
;         if (old + 1u == (gen + 1u) * nloc) {
;             __builtin_amdgcn_fence(__ATOMIC_RELEASE, "agent");
;             asm volatile("s_waitcnt vmcnt(0)" ::: "memory");
;             const unsigned og = xb_add(&bar[XB_TOP], 1u);
;             const unsigned tg = og / nx;
;             if (og + 1u == (tg + 1u) * nx) xb_add(&bar[XB_TOPGEN], 1u);
;             else XB_SPIN(xb_ld(&bar[XB_TOPGEN]) == tg, bar);
;             __builtin_amdgcn_fence(__ATOMIC_ACQUIRE, "agent");
;             xb_add(&bar[XB_XGEN(b.x)], 1u);
;             asm volatile("s_waitcnt vmcnt(0)" ::: "memory");
;         } else {
;             XB_SPIN(xb_ld(&bar[XB_TOPGEN]) == gen, bar);
.LBB0_148:
	s_or_b64 exec, exec, s[14:15]
	v_cvt_f32_u32_e32 v4, v2
	s_waitcnt vmcnt(0)
	v_readfirstlane_b32 s3, v3
	v_sub_u32_e32 v3, 0, v2
	v_rcp_iflag_f32_e32 v4, v4
	v_add_u32_e32 v5, s3, v1
	v_mul_f32_e32 v4, 0x4f7ffffe, v4
	v_cvt_u32_f32_e32 v4, v4
	v_mul_lo_u32 v1, v3, v4
	v_mul_hi_u32 v1, v4, v1
	v_add_u32_e32 v1, v4, v1
	v_mul_hi_u32 v1, v5, v1
	v_mul_lo_u32 v3, v1, v2
	v_sub_u32_e32 v3, v5, v3
	v_add_u32_e32 v4, 1, v1
	v_cmp_ge_u32_e32 vcc, v3, v2
	s_nop 1
	v_cndmask_b32_e32 v1, v1, v4, vcc
	v_sub_u32_e32 v4, v3, v2
	v_cndmask_b32_e32 v3, v3, v4, vcc
	v_add_u32_e32 v4, 1, v1
	v_cmp_ge_u32_e32 vcc, v3, v2
	v_add_u32_e32 v3, 1, v5
	s_nop 0
	v_cndmask_b32_e32 v1, v1, v4, vcc
	v_mul_lo_u32 v4, v2, v1
	v_add_u32_e32 v2, v4, v2
	v_cmp_ne_u32_e32 vcc, v3, v2
	s_and_saveexec_b64 s[12:13], vcc
	s_xor_b64 s[12:13], exec, s[12:13]
	s_cbranch_execz .LBB0_162
	s_waitcnt lgkmcnt(0)
	v_mul_lo_u32 v6, v0, v1
	v_add_u32_e32 v6, v6, v0
	v_mov_b32_e32 v0, 0x4000
	global_load_dword v0, v0, s[80:81] offset:1024 sc1
	s_add_u32 s18, s80, 0x4400
	s_addc_u32 s19, s81, 0
	s_waitcnt vmcnt(0)
	v_cmp_lt_u32_e32 vcc, v0, v6
	s_and_saveexec_b64 s[14:15], vcc
	s_cbranch_execz .LBB0_161
	s_add_u32 s16, s80, 0x1200
	s_addc_u32 s17, s81, 0
	s_mov_b32 s3, 1
	s_mov_b64 s[20:21], 0
	v_mov_b32_e32 v0, 0
	s_branch .LBB0_152

; __device__ __forceinline__ unsigned xb_ld(unsigned* p)              { return __hip_atomic_load(p, __ATOMIC_RELAXED, __HIP_MEMORY_SCOPE_AGENT); }
; #define XB_SPIN(cond, bar) do { unsigned _sp = 0; while (cond) { __builtin_amdgcn_s_sleep(1); \
;     if ((++_sp & 255u) == 0u) { if (xb_ld(&(bar)[XB_TMO])) break; if (_sp > XB_SPIN_CAP) { atomicAdd(&(bar)[XB_TMO], 1u); break; } } } } while (0)
; __device__ __forceinline__ void xcd_barrier(const XcdBarrier& b) {
;     ...
;         } else {
;             XB_SPIN(xb_ld(&bar[XB_TOPGEN]) == gen, bar);
;             __builtin_amdgcn_fence(__ATOMIC_ACQUIRE, "agent");
.LBB0_156:
	global_load_dword v2, v0, s[18:19] sc1
	s_add_i32 s3, s3, 1
	s_mov_b64 s[26:27], -1
	s_waitcnt vmcnt(0)
	v_cmp_ge_u32_e32 vcc, v2, v6
	s_orn2_b64 s[24:25], vcc, exec
	s_branch .LBB0_151

; __device__ __forceinline__ unsigned xb_ld(unsigned* p)              { return __hip_atomic_load(p, __ATOMIC_RELAXED, __HIP_MEMORY_SCOPE_AGENT); }
; __device__ __forceinline__ unsigned xb_add(unsigned* p, unsigned v) { return __hip_atomic_fetch_add(p, v, __ATOMIC_RELAXED, __HIP_MEMORY_SCOPE_AGENT); }
; #define XB_SPIN(cond, bar) do { unsigned _sp = 0; while (cond) { __builtin_amdgcn_s_sleep(1); \
;     if ((++_sp & 255u) == 0u) { if (xb_ld(&(bar)[XB_TMO])) break; if (_sp > XB_SPIN_CAP) { atomicAdd(&(bar)[XB_TMO], 1u); break; } } } } while (0)
; __device__ __forceinline__ void xcd_barrier(const XcdBarrier& b) {
;     ...
;             const unsigned og = xb_add(&bar[XB_TOP], 1u);
;             const unsigned tg = og / nx;
;             if (og + 1u == (tg + 1u) * nx) xb_add(&bar[XB_TOPGEN], 1u);
;             else XB_SPIN(xb_ld(&bar[XB_TOPGEN]) == tg, bar);
.LBB0_165:
	s_or_b64 exec, exec, s[14:15]
	v_cvt_f32_u32_e32 v3, v0
	s_waitcnt vmcnt(0)
	v_readfirstlane_b32 s3, v2
	s_add_u32 s14, s80, 0x4500
	s_addc_u32 s15, s81, 0
	s_add_u32 s30, s80, 0x4400
	s_addc_u32 s31, s81, 0
	v_rcp_iflag_f32_e32 v3, v3
	v_add_u32_e32 v1, s3, v1
	v_add_u32_e32 v4, 1, v1
	s_mov_b64 s[16:17], -1
	v_mul_f32_e32 v2, 0x4f7ffffe, v3
	v_cvt_u32_f32_e32 v2, v2
	v_sub_u32_e32 v3, 0, v0
	v_mul_lo_u32 v3, v3, v2
	v_mul_hi_u32 v3, v2, v3
	v_add_u32_e32 v2, v2, v3
	v_mul_hi_u32 v2, v1, v2
	v_mul_lo_u32 v3, v2, v0
	v_sub_u32_e32 v1, v1, v3
	v_add_u32_e32 v5, 1, v2
	v_cmp_ge_u32_e32 vcc, v1, v0
	v_sub_u32_e32 v3, v1, v0
	s_nop 0
	v_cndmask_b32_e32 v2, v2, v5, vcc
	v_cndmask_b32_e32 v1, v1, v3, vcc
	v_add_u32_e32 v3, 1, v2
	v_cmp_ge_u32_e32 vcc, v1, v0
	s_nop 1
	v_cndmask_b32_e32 v2, v2, v3, vcc
	v_mul_lo_u32 v1, v0, v2
	v_add_u32_e32 v0, v1, v0
	v_cmp_ne_u32_e32 vcc, v4, v0
	v_mov_b32_e32 v6, v0
	v_mov_b64_e32 v[0:1], s[14:15]
	s_and_saveexec_b64 s[12:13], vcc
	s_cbranch_execz .LBB0_177
	v_mov_b32_e32 v0, 0
	global_load_dword v1, v0, s[30:31] sc1
	s_mov_b64 s[20:21], 0
	s_waitcnt vmcnt(0)
	v_cmp_lt_u32_e32 vcc, v1, v6
	s_and_saveexec_b64 s[18:19], vcc
	s_cbranch_execz .LBB0_176
	s_add_u32 s16, s80, 0x1200
	s_addc_u32 s17, s81, 0
	s_mov_b32 s3, 1
	s_branch .LBB0_169

; __device__ __forceinline__ unsigned xb_ld(unsigned* p)              { return __hip_atomic_load(p, __ATOMIC_RELAXED, __HIP_MEMORY_SCOPE_AGENT); }
; #define XB_SPIN(cond, bar) do { unsigned _sp = 0; while (cond) { __builtin_amdgcn_s_sleep(1); \
;     if ((++_sp & 255u) == 0u) { if (xb_ld(&(bar)[XB_TMO])) break; if (_sp > XB_SPIN_CAP) { atomicAdd(&(bar)[XB_TMO], 1u); break; } } } } while (0)
; __device__ __forceinline__ void xcd_barrier(const XcdBarrier& b) {
;     ...
;             else XB_SPIN(xb_ld(&bar[XB_TOPGEN]) == tg, bar);
.LBB0_173:
	global_load_dword v1, v0, s[30:31] sc1
	s_add_i32 s3, s3, 1
	s_mov_b64 s[24:25], -1
	s_waitcnt vmcnt(0)
	v_cmp_ge_u32_e32 vcc, v1, v6
	s_orn2_b64 s[28:29], vcc, exec
	s_branch .LBB0_168
